# static s_setprio 1 for the trailing half (waves 4-7) during GEMM phases, no per-phase flips
# speedup vs baseline: 1.0002x; 1.0002x over previous
.LBB0_153:
	s_mul_i32 s0, s56, 9
	v_writelane_b32 v253, s0, 55
	s_add_i32 s0, s0, 1
	s_cmp_le_i32 s86, s0
	s_cselect_b64 s[2:3], -1, 0
	s_cmp_lt_i32 s0, s87
	s_cselect_b64 s[18:19], -1, 0
	s_and_b64 s[20:21], s[2:3], s[18:19]
	s_andn2_b64 vcc, exec, s[20:21]
	s_cbranch_vccnz .LBB0_172
	v_mov_b32_e32 v0, v242
	s_load_dword s9, s[54:55], 0x0
	s_mov_b32 s11, s76
	v_mov_b32_e32 v4, v242
	s_waitcnt lgkmcnt(0)
	s_cmpk_gt_i32 s11, 0x6ff
	v_readfirstlane_b32 s3, v4
	s_cbranch_scc1 .LBB0_172
	v_lshlrev_b32_e32 v0, 4, v4
	v_add_u32_e32 v1, 0x2000, v0
	v_ashrrev_i32_e32 v2, 31, v1
	v_lshrrev_b32_e32 v2, 22, v2
	v_add_u32_e32 v2, v1, v2
	s_mul_i32 s0, s56, 0x1600000
	v_ashrrev_i32_e32 v2, 10, v2
	s_add_u32 s0, s84, s0
	v_mul_i32_i24_e32 v3, 0x400, v2
	s_addc_u32 s2, s85, 0
	v_sub_u32_e32 v1, v1, v3
	s_add_u32 s17, s0, 0x400000
	v_lshrrev_b32_e32 v3, 4, v1
	s_addc_u32 s18, s2, 0
	v_bitop3_b32 v1, v3, v1, 32 bitop3:0x6c
	s_ashr_i32 s33, s11, 31
	v_ashrrev_i32_e32 v3, 31, v1
	s_lshr_b32 s0, s33, 29
	v_lshrrev_b32_e32 v3, 26, v3
	s_add_i32 s0, s11, s0
	s_ashr_i32 s2, s3, 6
	v_add_u32_e32 v3, v1, v3
	v_lshlrev_b32_e32 v6, 3, v2
	s_ashr_i32 s22, s0, 3
	s_and_b32 s0, s0, -8
	s_ashr_i32 s26, s3, 8
	s_lshl_b32 s19, s2, 10
	v_ashrrev_i32_e32 v5, 6, v3
	v_and_b32_e32 v6, -16, v6
	v_and_b32_e32 v3, 0xc0, v3
	s_sub_i32 s0, s11, s0
	v_add_u32_e32 v8, v5, v6
	v_lshlrev_b32_e32 v2, 5, v2
	v_sub_u32_e32 v1, v1, v3
	s_cmp_lt_i32 s0, 0
	s_movk_i32 s23, 0xe1
	v_lshrrev_b32_e32 v9, 2, v8
	v_lshlrev_b32_e32 v10, 1, v8
	v_and_b32_e32 v2, 32, v2
	v_ashrrev_i16_sdwa v1, v243, sext(v1) dst_sel:DWORD dst_unused:UNUSED_PAD src0_sel:DWORD src1_sel:BYTE_0
	s_cselect_b32 s23, s23, 0xe0
	v_and_b32_e32 v7, 3, v5
	v_and_b32_e32 v9, 4, v9
	v_and_b32_e32 v10, 0x1fffd8, v10
	v_add_u32_sdwa v1, v2, sext(v1) dst_sel:DWORD dst_unused:UNUSED_PAD src0_sel:DWORD src1_sel:WORD_0
	s_mul_i32 s0, s0, s23
	v_or3_b32 v7, v7, v9, v10
	v_lshlrev_b32_e32 v2, 1, v1
	v_lshlrev_b32_e32 v1, 3, v1
	s_add_i32 s0, s0, s22
	v_lshl_add_u32 v128, v7, 11, v2
	v_and_b32_e32 v7, 0x3ffff00, v1
	s_mul_hi_i32 s22, s0, 0x92492493
	v_add_u32_e32 v1, v7, v8
	v_and_b32_e32 v8, 62, v2
	s_add_i32 s22, s22, s0
	v_lshl_or_b32 v130, v1, 6, v8
	v_bfe_i32 v1, v4, 27, 1
	s_lshr_b32 s23, s22, 31
	s_ashr_i32 s22, s22, 5
	v_lshrrev_b32_e32 v1, 22, v1
	s_add_i32 s22, s22, s23
	v_add_u32_e32 v1, v0, v1
	s_lshl_b32 s23, s22, 3
	s_mul_i32 s22, s22, 56
	v_and_b32_e32 v1, 0xfffffc00, v1
	s_sub_i32 s22, s0, s22
	v_sub_u32_e32 v0, v0, v1
	s_bfe_i32 s0, s22, 0x80000
	v_lshrrev_b32_e32 v1, 4, v0
	v_ashrrev_i32_e32 v3, 31, v4
	s_bfe_u32 s0, s0, 0x3000c
	v_bitop3_b32 v0, v1, v0, 32 bitop3:0x6c
	v_lshrrev_b32_e32 v3, 26, v3
	s_add_i32 s24, s22, s0
	v_ashrrev_i32_e32 v1, 31, v0
	v_add_u32_e32 v3, v4, v3
	s_bfe_i32 s0, s24, 0x80000
	s_and_b32 s24, s24, 0xf8
	v_lshrrev_b32_e32 v1, 26, v1
	v_ashrrev_i32_e32 v3, 6, v3
	s_sub_i32 s22, s22, s24
	v_add_u32_e32 v1, v0, v1
	v_lshlrev_b32_e32 v10, 3, v3
	s_sext_i32_i16 s0, s0
	s_sext_i32_i8 s22, s22
	v_ashrrev_i32_e32 v9, 6, v1
	v_and_b32_e32 v10, -16, v10
	v_and_b32_e32 v1, 0xc0, v1
	s_lshr_b32 s0, s0, 3
	s_add_i32 s38, s23, s22
	v_add_u32_e32 v12, v9, v10
	v_lshlrev_b32_e32 v3, 5, v3
	v_sub_u32_e32 v0, v0, v1
	s_ashr_i32 s39, s38, 31
	s_bfe_i64 s[24:25], s[0:1], 0x100000
	v_lshrrev_b32_e32 v11, 2, v12
	v_lshlrev_b32_e32 v13, 1, v12
	v_and_b32_e32 v3, 32, v3
	v_ashrrev_i16_sdwa v0, v243, sext(v0) dst_sel:DWORD dst_unused:UNUSED_PAD src0_sel:DWORD src1_sel:BYTE_0
	s_lshl_b64 s[22:23], s[38:39], 19
	s_lshl_b64 s[24:25], s[24:25], 19
	v_and_b32_e32 v2, 3, v9
	v_and_b32_e32 v11, 4, v11
	v_and_b32_e32 v13, 0x1fffd8, v13
	v_add_u32_sdwa v0, v3, sext(v0) dst_sel:DWORD dst_unused:UNUSED_PAD src0_sel:DWORD src1_sel:WORD_0
	s_add_u32 s40, s17, s24
	v_or3_b32 v2, v2, v11, v13
	v_lshlrev_b32_e32 v1, 1, v0
	s_addc_u32 s41, s18, s25
	s_add_i32 s46, s19, 0
	v_lshl_add_u32 v132, v2, 11, v1
	s_add_i32 m0, s46, 0x10000
	v_lshlrev_b32_e32 v0, 3, v0
	global_load_lds_dwordx4 v132, s[40:41]
	s_add_i32 m0, s46, 0x12000
	s_add_u32 s24, s40, 0x10000
	global_load_lds_dwordx4 v128, s[40:41]
	s_addc_u32 s25, s41, 0
	s_add_i32 m0, s46, 0x14000
	v_and_b32_e32 v11, 0x3ffff00, v0
	global_load_lds_dwordx4 v132, s[24:25]
	s_add_i32 m0, s46, 0x16000
	s_add_u32 s42, s62, s22
	v_add_u32_e32 v0, v11, v12
	v_and_b32_e32 v12, 62, v1
	s_addc_u32 s43, s63, s23
	s_add_i32 s47, s46, 0x2000
	v_lshl_or_b32 v134, v0, 6, v12
	global_load_lds_dwordx4 v128, s[24:25]
	s_mov_b32 m0, s46
	s_add_u32 s22, s42, 0x2000
	global_load_lds_dwordx4 v134, s[42:43]
	s_mov_b32 m0, s47
	s_addc_u32 s23, s43, 0
	s_add_i32 s48, s46, 0x4000
	global_load_lds_dwordx4 v130, s[42:43]
	s_mov_b32 m0, s48
	s_add_i32 s49, s46, 0x6000
	global_load_lds_dwordx4 v134, s[22:23]
	s_mov_b32 m0, s49
	v_mov_b32_e32 v133, v209
	global_load_lds_dwordx4 v130, s[22:23]
	v_mov_b32_e32 v129, v209
	s_cmp_eq_u32 s26, 1
	s_mov_b64 s[80:81], s[54:55]
	s_mov_b32 s54, s56
	v_lshl_add_u64 v[0:1], s[40:41], 0, v[132:133]
	s_cselect_b64 s[22:23], -1, 0
	s_cmp_lg_u32 s26, 1
	v_lshl_add_u64 v[2:3], s[40:41], 0, v[128:129]
	s_cbranch_scc1 .LBB0_157
	s_setprio 1
	s_barrier

.LBB0_172:
	s_setprio 0
	v_readlane_b32 s0, v253, 55
	s_add_i32 s0, s0, 2
	s_cmp_lt_i32 s0, s87
	s_cselect_b64 s[22:23], -1, 0
	s_and_b64 s[2:3], s[20:21], s[22:23]
	v_readlane_b32 s50, v254, 32
	s_andn2_b64 vcc, exec, s[2:3]
	v_readlane_b32 s51, v254, 33
	s_movk_i32 s46, 0x5000
	s_mov_b32 s47, 0x1a000000
	s_mov_b64 s[38:39], 0x1000
	s_cbranch_vccnz .LBB0_222
	s_waitcnt vmcnt(0)
	s_barrier
	s_and_saveexec_b64 s[20:21], s[48:49]
	s_cbranch_execz .LBB0_221
	v_readlane_b32 s2, v253, 20
	s_waitcnt vmcnt(0) expcnt(0) lgkmcnt(0)
	s_nop 0
	v_mov_b32_e32 v0, s2
	ds_read_b32 v2, v0
	v_readlane_b32 s2, v253, 21
	s_waitcnt lgkmcnt(0)
	v_cmp_ne_u32_e32 vcc, 0, v2
	v_mov_b32_e32 v0, s2
	ds_read_b32 v0, v0
	s_cbranch_vccnz .LBB0_189
	s_load_dwordx2 s[2:3], s[54:55], 0x0
	s_load_dword s9, s[54:55], 0x8
	s_waitcnt lgkmcnt(0)
	s_mul_i32 s2, s3, s2
	s_mul_i32 s2, s2, s9
	s_mov_b32 s3, 1
	s_branch .LBB0_177

.LBB0_421:
	s_andn2_b64 vcc, exec, s[24:25]
	s_cbranch_vccnz .LBB0_509
	v_ashrrev_i32_e32 v1, 31, v9
	v_lshrrev_b32_e32 v1, 26, v1
	v_add_u32_e32 v1, v9, v1
	v_ashrrev_i32_e32 v8, 6, v1
	v_bfe_i32 v1, v9, 27, 1
	v_lshlrev_b32_e32 v0, 4, v9
	v_lshrrev_b32_e32 v1, 22, v1
	v_add_u32_e32 v1, v0, v1
	v_and_b32_e32 v1, 0xfffffc00, v1
	v_sub_u32_e32 v1, v0, v1
	v_lshrrev_b32_e32 v2, 4, v1
	v_bitop3_b32 v1, v2, v1, 32 bitop3:0x6c
	v_ashrrev_i32_e32 v3, 31, v1
	v_lshrrev_b32_e32 v3, 26, v3
	v_add_u32_e32 v3, v1, v3
	s_mul_i32 s0, s56, 0x1600000
	v_lshlrev_b32_e32 v2, 3, v8
	v_ashrrev_i32_e32 v10, 6, v3
	v_and_b32_e32 v3, 0xc0, v3
	s_add_u32 s0, s84, s0
	v_and_b32_e32 v2, -16, v2
	v_sub_u32_e32 v1, v1, v3
	s_addc_u32 s2, s85, 0
	v_add_u32_e32 v2, v10, v2
	v_ashrrev_i16_sdwa v1, v243, sext(v1) dst_sel:DWORD dst_unused:UNUSED_PAD src0_sel:DWORD src1_sel:BYTE_0
	s_add_u32 s18, s0, 0x780000
	v_lshlrev_b32_e32 v4, 5, v8
	v_bfe_i32 v11, v1, 0, 16
	v_lshlrev_b32_e32 v1, 1, v2
	v_lshrrev_b32_e32 v3, 2, v2
	v_and_b32_e32 v5, 3, v10
	s_mov_b32 s0, 0x1fffe0
	v_and_b32_e32 v4, 32, v4
	v_and_b32_e32 v1, 24, v1
	v_and_b32_e32 v3, 4, v3
	v_and_or_b32 v5, v2, s0, v5
	v_or3_b32 v1, v5, v3, v1
	v_add_lshl_u32 v3, v4, v11, 1
	v_add_u32_e32 v0, 0x2000, v0
	v_lshl_add_u32 v208, v1, 11, v3
	v_ashrrev_i32_e32 v1, 31, v0
	v_lshrrev_b32_e32 v1, 22, v1
	v_add_u32_e32 v1, v0, v1
	v_ashrrev_i32_e32 v12, 10, v1
	v_mul_i32_i24_e32 v1, 0x400, v12
	v_sub_u32_e32 v0, v0, v1
	v_lshrrev_b32_e32 v1, 4, v0
	v_bitop3_b32 v0, v1, v0, 32 bitop3:0x6c
	v_lshl_add_u32 v218, v2, 11, v3
	v_ashrrev_i32_e32 v2, 31, v0
	v_lshrrev_b32_e32 v2, 26, v2
	v_add_u32_e32 v2, v0, v2
	s_addc_u32 s19, s2, 0
	s_ashr_i32 s3, s30, 6
	v_lshlrev_b32_e32 v1, 3, v12
	v_ashrrev_i32_e32 v13, 6, v2
	v_and_b32_e32 v2, 0xc0, v2
	s_ashr_i32 s23, s22, 31
	s_ashr_i32 s29, s28, 31
	v_and_b32_e32 v1, -16, v1
	v_sub_u32_e32 v0, v0, v2
	s_ashr_i32 s2, s30, 8
	s_lshl_b32 s64, s3, 10
	s_lshl_b64 s[24:25], s[22:23], 19
	s_lshl_b64 s[26:27], s[28:29], 19
	v_add_u32_e32 v1, v13, v1
	v_ashrrev_i16_sdwa v0, v243, sext(v0) dst_sel:DWORD dst_unused:UNUSED_PAD src0_sel:DWORD src1_sel:BYTE_0
	s_add_u32 s78, s18, s26
	v_lshlrev_b32_e32 v3, 5, v12
	v_bfe_i32 v14, v0, 0, 16
	v_lshlrev_b32_e32 v0, 1, v1
	v_lshrrev_b32_e32 v2, 2, v1
	v_and_b32_e32 v4, 3, v13
	s_addc_u32 s79, s19, s27
	s_add_i32 s33, s64, 0
	v_and_b32_e32 v3, 32, v3
	v_and_b32_e32 v0, 24, v0
	v_and_b32_e32 v2, 4, v2
	v_and_or_b32 v4, v1, s0, v4
	s_add_i32 m0, s33, 0x10000
	v_or3_b32 v0, v4, v2, v0
	v_add_lshl_u32 v2, v3, v14, 1
	global_load_lds_dwordx4 v208, s[78:79]
	s_add_i32 m0, s33, 0x12000
	v_lshl_add_u32 v222, v0, 11, v2
	s_add_u32 s26, s78, 0x40000
	global_load_lds_dwordx4 v222, s[78:79]
	s_addc_u32 s27, s79, 0
	s_add_i32 m0, s33, 0x14000
	v_lshl_add_u32 v220, v1, 11, v2
	global_load_lds_dwordx4 v208, s[26:27]
	s_add_i32 m0, s33, 0x16000
	v_mov_b32_e32 v223, v209
	global_load_lds_dwordx4 v222, s[26:27]
	v_readlane_b32 s26, v253, 4
	v_readlane_b32 s27, v253, 5
	s_add_u32 s34, s26, s24
	s_addc_u32 s35, s27, s25
	s_add_i32 s11, s33, 0x2000
	s_mov_b32 m0, s33
	s_add_u32 s24, s34, 0x40000
	global_load_lds_dwordx4 v218, s[34:35]
	s_mov_b32 m0, s11
	s_addc_u32 s25, s35, 0
	s_add_i32 s65, s33, 0x4000
	global_load_lds_dwordx4 v220, s[34:35]
	s_mov_b32 m0, s65
	s_add_i32 s66, s33, 0x6000
	global_load_lds_dwordx4 v218, s[24:25]
	s_mov_b32 m0, s66
	v_mov_b32_e32 v219, v209
	global_load_lds_dwordx4 v220, s[24:25]
	v_mov_b32_e32 v221, v209
	s_cmp_eq_u32 s2, 1
	v_lshl_add_u64 v[6:7], s[78:79], 0, v[208:209]
	v_lshl_add_u64 v[4:5], s[78:79], 0, v[222:223]
	v_lshl_add_u64 v[0:1], s[34:35], 0, v[218:219]
	s_cselect_b64 s[24:25], -1, 0
	s_cmp_lg_u32 s2, 1
	v_lshl_add_u64 v[2:3], s[34:35], 0, v[220:221]
	s_cbranch_scc1 .LBB0_424
	s_setprio 1
	s_barrier

.LBB0_509:
	s_setprio 0
	v_readlane_b32 s0, v253, 55
	s_add_i32 s0, s0, 6
	s_cmp_ge_i32 s0, s87
	s_cbranch_scc1 .LBB0_559
	s_waitcnt vmcnt(0)
	s_barrier
	s_and_saveexec_b64 s[22:23], s[48:49]
	s_cbranch_execz .LBB0_558
	v_readlane_b32 s0, v253, 20
	s_waitcnt vmcnt(0) expcnt(0) lgkmcnt(0)
	s_nop 0
	v_mov_b32_e32 v0, s0
	ds_read_b32 v2, v0
	v_readlane_b32 s0, v253, 21
	s_waitcnt lgkmcnt(0)
	v_cmp_ne_u32_e32 vcc, 0, v2
	v_mov_b32_e32 v0, s0
	ds_read_b32 v0, v0
	s_cbranch_vccnz .LBB0_526
	s_load_dwordx2 s[2:3], s[54:55], 0x0
	s_load_dword s0, s[54:55], 0x8
	s_waitcnt lgkmcnt(0)
	s_mul_i32 s2, s3, s2
	s_mul_i32 s0, s2, s0
	s_mov_b32 s2, 1
	s_branch .LBB0_514

.LBB0_561:
	s_andn2_b64 vcc, exec, s[22:23]
	s_cbranch_vccnz .LBB0_630
	v_mov_b32_e32 v0, v242
	s_load_dword s9, s[54:55], 0x0
	s_mov_b32 s11, s76
	v_mov_b32_e32 v12, v242
	s_waitcnt lgkmcnt(0)
	s_cmpk_gt_i32 s11, 0x15ff
	v_readfirstlane_b32 s3, v12
	s_cbranch_scc1 .LBB0_580
	v_lshlrev_b32_e32 v0, 4, v12
	v_add_u32_e32 v1, 0x2000, v0
	v_ashrrev_i32_e32 v2, 31, v1
	v_lshrrev_b32_e32 v2, 22, v2
	v_add_u32_e32 v2, v1, v2
	v_ashrrev_i32_e32 v2, 10, v2
	v_mul_i32_i24_e32 v3, 0x400, v2
	v_sub_u32_e32 v1, v1, v3
	v_lshrrev_b32_e32 v3, 4, v1
	v_bitop3_b32 v1, v3, v1, 32 bitop3:0x6c
	v_ashrrev_i32_e32 v3, 31, v1
	v_lshrrev_b32_e32 v3, 26, v3
	s_mul_i32 s0, s56, 0x1600000
	v_add_u32_e32 v3, v1, v3
	v_lshlrev_b32_e32 v5, 3, v2
	s_add_u32 s0, s84, s0
	v_ashrrev_i32_e32 v4, 6, v3
	v_and_b32_e32 v5, -16, v5
	v_and_b32_e32 v3, 0xc0, v3
	s_addc_u32 s2, s85, 0
	v_add_u32_e32 v7, v4, v5
	v_lshlrev_b32_e32 v2, 5, v2
	v_sub_u32_e32 v1, v1, v3
	s_add_u32 s17, s0, 0x980000
	v_and_b32_e32 v6, 3, v4
	s_mov_b32 s0, 0x1fffe0
	v_lshrrev_b32_e32 v8, 2, v7
	v_lshlrev_b32_e32 v9, 1, v7
	v_and_b32_e32 v2, 32, v2
	v_ashrrev_i16_sdwa v1, v243, sext(v1) dst_sel:DWORD dst_unused:UNUSED_PAD src0_sel:DWORD src1_sel:BYTE_0
	v_and_or_b32 v6, v7, s0, v6
	v_and_b32_e32 v8, 4, v8
	v_and_b32_e32 v9, 24, v9
	v_add_u32_sdwa v1, v2, sext(v1) dst_sel:DWORD dst_unused:UNUSED_PAD src0_sel:DWORD src1_sel:WORD_0
	v_or3_b32 v6, v6, v8, v9
	v_lshlrev_b32_e32 v2, 1, v1
	v_lshlrev_b32_e32 v1, 3, v1
	v_lshl_add_u32 v128, v6, 11, v2
	v_and_b32_e32 v6, 0x3ffff00, v1
	v_add_u32_e32 v1, v6, v7
	v_and_b32_e32 v7, 62, v2
	v_lshl_or_b32 v130, v1, 6, v7
	v_bfe_i32 v1, v12, 27, 1
	v_lshrrev_b32_e32 v1, 22, v1
	v_add_u32_e32 v1, v0, v1
	v_and_b32_e32 v1, 0xfffffc00, v1
	v_sub_u32_e32 v0, v0, v1
	v_lshrrev_b32_e32 v1, 4, v0
	v_ashrrev_i32_e32 v2, 31, v12
	v_bitop3_b32 v0, v1, v0, 32 bitop3:0x6c
	v_lshrrev_b32_e32 v2, 26, v2
	v_ashrrev_i32_e32 v1, 31, v0
	v_add_u32_e32 v2, v12, v2
	v_lshrrev_b32_e32 v1, 26, v1
	v_ashrrev_i32_e32 v2, 6, v2
	v_add_u32_e32 v1, v0, v1
	v_lshlrev_b32_e32 v3, 3, v2
	v_ashrrev_i32_e32 v8, 6, v1
	v_and_b32_e32 v9, -16, v3
	s_addc_u32 s18, s2, 0
	v_add_u32_e32 v3, v8, v9
	v_and_b32_e32 v10, 3, v8
	s_ashr_i32 s33, s11, 31
	v_and_or_b32 v10, v3, s0, v10
	s_lshr_b32 s0, s33, 29
	s_add_i32 s0, s11, s0
	s_ashr_i32 s25, s3, 6
	s_ashr_i32 s2, s0, 3
	s_and_b32 s0, s0, -8
	s_ashr_i32 s24, s3, 8
	s_lshl_b32 s19, s25, 10
	s_sub_i32 s0, s11, s0
	s_cmp_lt_i32 s0, 0
	s_movk_i32 s22, 0x2c1
	s_cselect_b32 s22, s22, 0x2c0
	s_mul_i32 s0, s0, s22
	s_add_i32 s0, s0, s2
	s_mul_hi_i32 s2, s0, 0x2e8ba2e9
	s_lshr_b32 s22, s2, 31
	s_ashr_i32 s2, s2, 5
	s_add_i32 s2, s2, s22
	s_lshl_b32 s22, s2, 3
	s_mulk_i32 s2, 0xb0
	s_sub_i32 s2, s0, s2
	s_bfe_u32 s0, s2, 0x3001c
	s_add_i32 s23, s2, s0
	s_sext_i32_i16 s0, s23
	s_and_b32 s23, s23, 0xfff8
	s_sub_i32 s2, s2, s23
	s_sext_i32_i16 s2, s2
	v_and_b32_e32 v1, 0xc0, v1
	s_lshr_b32 s0, s0, 3
	s_add_i32 s38, s22, s2
	v_lshlrev_b32_e32 v2, 5, v2
	v_sub_u32_e32 v0, v0, v1
	s_ashr_i32 s39, s38, 31
	s_bfe_i64 s[26:27], s[0:1], 0x100000
	v_lshrrev_b32_e32 v11, 2, v3
	v_lshlrev_b32_e32 v13, 1, v3
	v_and_b32_e32 v2, 32, v2
	v_ashrrev_i16_sdwa v0, v243, sext(v0) dst_sel:DWORD dst_unused:UNUSED_PAD src0_sel:DWORD src1_sel:BYTE_0
	s_lshl_b64 s[22:23], s[38:39], 19
	s_lshl_b64 s[26:27], s[26:27], 19
	v_and_b32_e32 v11, 4, v11
	v_and_b32_e32 v13, 24, v13
	v_add_u32_sdwa v0, v2, sext(v0) dst_sel:DWORD dst_unused:UNUSED_PAD src0_sel:DWORD src1_sel:WORD_0
	s_add_u32 s40, s17, s26
	v_or3_b32 v10, v10, v11, v13
	v_lshlrev_b32_e32 v1, 1, v0
	s_addc_u32 s41, s18, s27
	s_add_i32 s48, s19, 0
	v_lshl_add_u32 v132, v10, 11, v1
	s_add_i32 m0, s48, 0x10000
	v_lshlrev_b32_e32 v0, 3, v0
	global_load_lds_dwordx4 v132, s[40:41]
	s_add_i32 m0, s48, 0x12000
	s_add_u32 s26, s40, 0x40000
	global_load_lds_dwordx4 v128, s[40:41]
	s_addc_u32 s27, s41, 0
	s_add_i32 m0, s48, 0x14000
	v_and_b32_e32 v10, 0x3ffff00, v0
	global_load_lds_dwordx4 v132, s[26:27]
	s_add_i32 m0, s48, 0x16000
	s_add_u32 s42, s62, s22
	v_add_u32_e32 v0, v10, v3
	v_and_b32_e32 v11, 62, v1
	s_addc_u32 s43, s63, s23
	s_add_i32 s49, s48, 0x2000
	v_lshl_or_b32 v134, v0, 6, v11
	global_load_lds_dwordx4 v128, s[26:27]
	s_mov_b32 m0, s48
	s_add_u32 s22, s42, 0x2000
	global_load_lds_dwordx4 v134, s[42:43]
	s_mov_b32 m0, s49
	s_addc_u32 s23, s43, 0
	s_add_i32 s52, s48, 0x4000
	global_load_lds_dwordx4 v130, s[42:43]
	s_mov_b32 m0, s52
	s_add_i32 s53, s48, 0x6000
	global_load_lds_dwordx4 v134, s[22:23]
	s_mov_b32 m0, s53
	v_mov_b32_e32 v133, v209
	global_load_lds_dwordx4 v130, s[22:23]
	v_mov_b32_e32 v129, v209
	s_cmp_eq_u32 s24, 1
	s_mov_b64 s[70:71], s[54:55]
	s_mov_b32 s54, s56
	v_lshl_add_u64 v[0:1], s[40:41], 0, v[132:133]
	s_cselect_b64 s[22:23], -1, 0
	s_cmp_lg_u32 s24, 1
	v_lshl_add_u64 v[2:3], s[40:41], 0, v[128:129]
	s_cbranch_scc1 .LBB0_565
	s_setprio 1
	s_barrier

.LBB0_580:
	s_setprio 0
	v_readlane_b32 s0, v253, 55
	s_add_i32 s0, s0, 8
	s_cmp_ge_i32 s0, s87
	s_cbranch_scc1 .LBB0_630
	s_waitcnt vmcnt(0)
	s_barrier
	s_and_saveexec_b64 s[22:23], s[48:49]
	s_cbranch_execz .LBB0_629
	v_readlane_b32 s2, v253, 20
	s_waitcnt vmcnt(0) expcnt(0) lgkmcnt(0)
	s_nop 0
	v_mov_b32_e32 v0, s2
	ds_read_b32 v2, v0
	v_readlane_b32 s2, v253, 21
	s_waitcnt lgkmcnt(0)
	v_cmp_ne_u32_e32 vcc, 0, v2
	v_mov_b32_e32 v0, s2
	ds_read_b32 v0, v0
	s_cbranch_vccnz .LBB0_597
	s_load_dwordx2 s[2:3], s[54:55], 0x0
	s_load_dword s9, s[54:55], 0x8
	s_waitcnt lgkmcnt(0)
	s_mul_i32 s2, s3, s2
	s_mul_i32 s2, s2, s9
	s_mov_b32 s3, 1
	s_branch .LBB0_585

.LBB0_637:
	s_andn2_b64 vcc, exec, s[28:29]
	s_cbranch_vccnz .LBB0_794
	v_bfe_i32 v2, v4, 27, 1
	v_lshlrev_b32_e32 v0, 4, v4
	v_lshrrev_b32_e32 v2, 22, v2
	v_ashrrev_i32_e32 v1, 31, v4
	v_add_u32_e32 v2, v0, v2
	v_lshrrev_b32_e32 v1, 26, v1
	v_and_b32_e32 v2, 0xfffffc00, v2
	v_add_u32_e32 v1, v4, v1
	v_sub_u32_e32 v2, v0, v2
	v_ashrrev_i32_e32 v1, 6, v1
	v_lshrrev_b32_e32 v3, 4, v2
	v_bitop3_b32 v2, v3, v2, 32 bitop3:0x6c
	v_lshlrev_b32_e32 v3, 3, v1
	v_and_b32_e32 v5, -16, v3
	v_ashrrev_i32_e32 v3, 31, v2
	v_lshrrev_b32_e32 v3, 26, v3
	v_add_u32_e32 v3, v2, v3
	s_mul_i32 s0, s56, 0x1600000
	v_ashrrev_i32_e32 v6, 6, v3
	v_and_b32_e32 v3, 0xc0, v3
	s_add_u32 s0, s84, s0
	v_lshlrev_b32_e32 v1, 5, v1
	v_sub_u32_e32 v2, v2, v3
	s_addc_u32 s2, s85, 0
	v_add_u32_e32 v8, v6, v5
	v_and_b32_e32 v1, 32, v1
	v_ashrrev_i16_sdwa v2, v243, sext(v2) dst_sel:DWORD dst_unused:UNUSED_PAD src0_sel:DWORD src1_sel:BYTE_0
	s_add_u32 s92, s0, 0x1480000
	v_add_u32_sdwa v1, v1, sext(v2) dst_sel:DWORD dst_unused:UNUSED_PAD src0_sel:DWORD src1_sel:WORD_0
	v_lshlrev_b32_e32 v2, 1, v8
	v_lshrrev_b32_e32 v3, 2, v8
	v_and_b32_e32 v7, 3, v6
	s_mov_b32 s0, 0xffffe0
	v_and_b32_e32 v2, 24, v2
	v_and_b32_e32 v3, 4, v3
	v_and_or_b32 v7, v8, s0, v7
	v_or3_b32 v2, v7, v3, v2
	v_lshlrev_b32_e32 v3, 3, v1
	v_and_b32_e32 v7, 0x3ffff00, v3
	v_mul_u32_u24_e32 v2, 0xb00, v2
	v_add_u32_e32 v0, 0x2000, v0
	v_add_u32_e32 v3, v7, v8
	v_lshlrev_b32_e32 v8, 1, v1
	v_add_lshl_u32 v208, v2, v1, 1
	v_ashrrev_i32_e32 v1, 31, v0
	v_lshrrev_b32_e32 v1, 22, v1
	v_add_u32_e32 v1, v0, v1
	v_ashrrev_i32_e32 v1, 10, v1
	v_mul_i32_i24_e32 v2, 0x400, v1
	v_sub_u32_e32 v0, v0, v2
	v_lshrrev_b32_e32 v2, 4, v0
	v_bitop3_b32 v0, v2, v0, 32 bitop3:0x6c
	v_lshlrev_b32_e32 v2, 3, v1
	v_and_b32_e32 v9, -16, v2
	v_ashrrev_i32_e32 v2, 31, v0
	v_lshrrev_b32_e32 v2, 26, v2
	v_add_u32_e32 v2, v0, v2
	v_ashrrev_i32_e32 v10, 6, v2
	v_and_b32_e32 v2, 0xc0, v2
	s_addc_u32 s93, s2, 0
	s_ashr_i32 s3, s11, 6
	v_and_b32_e32 v8, 62, v8
	v_lshlrev_b32_e32 v1, 5, v1
	v_sub_u32_e32 v0, v0, v2
	v_lshl_or_b32 v218, v3, 6, v8
	v_add_u32_e32 v3, v10, v9
	v_and_b32_e32 v1, 32, v1
	v_ashrrev_i16_sdwa v0, v243, sext(v0) dst_sel:DWORD dst_unused:UNUSED_PAD src0_sel:DWORD src1_sel:BYTE_0
	s_ashr_i32 s2, s11, 8
	s_lshl_b32 s94, s3, 10
	s_mul_i32 s19, s80, 0x160000
	v_add_u32_sdwa v0, v1, sext(v0) dst_sel:DWORD dst_unused:UNUSED_PAD src0_sel:DWORD src1_sel:WORD_0
	v_lshlrev_b32_e32 v1, 1, v3
	v_lshrrev_b32_e32 v2, 2, v3
	v_and_b32_e32 v11, 3, v10
	s_mul_hi_i32 s18, s80, 0x160000
	s_add_u32 s78, s92, s19
	v_and_b32_e32 v1, 24, v1
	v_and_b32_e32 v2, 4, v2
	v_and_or_b32 v11, v3, s0, v11
	s_addc_u32 s79, s93, s18
	s_add_i32 s95, s94, 0
	v_or3_b32 v1, v11, v2, v1
	s_add_i32 m0, s95, 0x10000
	v_mul_u32_u24_e32 v1, 0xb00, v1
	global_load_lds_dwordx4 v208, s[78:79]
	s_add_i32 m0, s95, 0x12000
	v_add_lshl_u32 v222, v1, v0, 1
	s_add_u32 s18, s78, 0xb0000
	global_load_lds_dwordx4 v222, s[78:79]
	s_addc_u32 s19, s79, 0
	s_add_i32 m0, s95, 0x14000
	v_lshlrev_b32_e32 v2, 3, v0
	s_mul_i32 s27, s26, 0x160000
	global_load_lds_dwordx4 v208, s[18:19]
	s_add_i32 m0, s95, 0x16000
	v_and_b32_e32 v11, 0x3ffff00, v2
	s_mul_hi_i32 s0, s26, 0x160000
	s_add_u32 s34, s50, s27
	v_add_u32_e32 v2, v11, v3
	v_lshlrev_b32_e32 v3, 1, v0
	global_load_lds_dwordx4 v222, s[18:19]
	s_addc_u32 s35, s51, s0
	s_add_i32 s18, s95, 0x2000
	v_and_b32_e32 v12, 62, v3
	s_mov_b32 m0, s95
	s_add_u32 s28, s34, 0x2000
	v_lshl_or_b32 v220, v2, 6, v12
	global_load_lds_dwordx4 v218, s[34:35]
	s_mov_b32 m0, s18
	s_addc_u32 s29, s35, 0
	s_add_i32 s19, s95, 0x4000
	global_load_lds_dwordx4 v220, s[34:35]
	s_mov_b32 m0, s19
	s_add_i32 s66, s95, 0x6000
	global_load_lds_dwordx4 v218, s[28:29]
	s_mov_b32 m0, s66
	v_mov_b32_e32 v223, v209
	global_load_lds_dwordx4 v220, s[28:29]
	s_cmp_eq_u32 s2, 1
	s_mov_b64 s[38:39], s[54:55]
	v_lshl_add_u64 v[0:1], s[78:79], 0, v[208:209]
	s_cselect_b64 s[28:29], -1, 0
	s_cmp_lg_u32 s2, 1
	v_lshl_add_u64 v[2:3], s[78:79], 0, v[222:223]
	s_cbranch_scc1 .LBB0_640
	s_setprio 1
	s_barrier

.LBB0_794:
	s_setprio 0
	v_readlane_b32 s2, v253, 24
	v_readlane_b32 s18, v253, 16
	v_readlane_b32 s3, v253, 25
	v_readlane_b32 s19, v253, 17
	s_and_b64 s[2:3], s[2:3], s[22:23]
	s_and_b64 s[18:19], s[24:25], s[18:19]
	s_and_b64 s[2:3], s[2:3], s[18:19]
	s_andn2_b64 vcc, exec, s[2:3]
	s_cbranch_vccnz .LBB0_152
	s_waitcnt vmcnt(0)
	s_waitcnt lgkmcnt(0)
	s_barrier
	s_and_saveexec_b64 s[18:19], s[48:49]
	s_cbranch_execz .LBB0_151
	v_readlane_b32 s0, v253, 20
	s_waitcnt vmcnt(0) expcnt(0) lgkmcnt(0)
	s_nop 0
	v_mov_b32_e32 v0, s0
	ds_read_b32 v2, v0
	v_readlane_b32 s0, v253, 21
	s_waitcnt lgkmcnt(0)
	v_cmp_ne_u32_e32 vcc, 0, v2
	v_mov_b32_e32 v0, s0
	ds_read_b32 v0, v0
	s_cbranch_vccnz .LBB0_811
	s_load_dwordx2 s[2:3], s[54:55], 0x0
	s_load_dword s0, s[54:55], 0x8
	s_waitcnt lgkmcnt(0)
	s_mul_i32 s2, s3, s2
	s_mul_i32 s0, s2, s0
	s_mov_b32 s2, 1
	s_branch .LBB0_799
